# P5+P7 epilogues restructured, s_nop pads between inline-asm VALU pairs removed (select_row counts, v_max3 chains), compress loop counted vmcnt instead of drain
# speedup vs baseline: 1.0198x; 1.0057x over previous
; #define CMP_LOAD(tk_, AR, BR) do { const int t_ = (tk_); if (t_ < 32) { _Pragma("unroll") for (int i = 0; i < 4; ++i) AR[i] = *(const u32x4*)(asrc + (size_t)i * 64 * 2048 + t_ * 64); \
;         if (bthr) BR = *(const u32x4*)(bsrc + (size_t)t_ * NZ); } } while (0)
; DI void compress_task(LAS unsigned char* lds, const bf16_t* Z, const bf16_t* W1t, const bf16_t* W2t, const float* bias1, bf16_t* KCC, bf16_t* VCT, int kv, int b, int hk, int nt4, int tid, int wave, int lane) {
;     ...
;     f32x16 acc = f16zero();
;     CMP_LOAD(0, a0, b0v); CMP_LOAD(1, a1, b1v);
;     for (int tk = 0; tk < 32; tk += 2) { CMP_STEP(tk, a0, b0v, 0); CMP_STEP(tk + 1, a1, b1v, 1); }
.LBB0_392:
	s_waitcnt vmcnt(4)
	ds_write_b128 v93, v[22:25]
	s_waitcnt vmcnt(6)
	ds_write_b128 v93, v[18:21] offset:8192
	s_waitcnt vmcnt(5)
	ds_write_b128 v93, v[26:29] offset:16384
	s_waitcnt vmcnt(4)
	ds_write_b128 v93, v[30:33] offset:24576
	s_and_saveexec_b64 s[8:9], s[4:5]
	ds_write_b128 v93, v[40:43] offset:32768
	s_or_b64 exec, exec, s[8:9]
	s_cmp_gt_u32 s12, 29
	s_cselect_b64 s[8:9], -1, 0
	s_and_b64 vcc, exec, s[8:9]
	v_lshl_add_u64 v[76:77], v[74:75], 0, v[66:67]
	s_waitcnt lgkmcnt(0)
	s_barrier
	s_cbranch_vccnz .Lcmp_noload
	v_add_co_u32_e32 v18, vcc, 0x40000, v76
	s_nop 1
	v_addc_co_u32_e32 v19, vcc, 0, v77, vcc
	v_add_co_u32_e32 v22, vcc, 0x80000, v76
	s_nop 1
	v_addc_co_u32_e32 v23, vcc, 0, v77, vcc
	v_add_co_u32_e32 v30, vcc, 0xc0000, v76
	global_load_dwordx4 v[18:21], v[18:19], off offset:256
	s_nop 0
	global_load_dwordx4 v[26:29], v[22:23], off offset:256
	v_addc_co_u32_e32 v31, vcc, 0, v77, vcc
	global_load_dwordx4 v[22:25], v[76:77], off offset:256
	s_nop 0
	global_load_dwordx4 v[30:33], v[30:31], off offset:256
	s_waitcnt vmcnt(4)
	s_and_saveexec_b64 s[10:11], s[4:5]
	s_cbranch_execz .LBB0_397
	v_lshl_add_u64 v[40:41], v[38:39], 0, v[66:67]
	v_add_co_u32_e32 v40, vcc, 0xe204000, v40
	s_nop 1
	v_addc_co_u32_e32 v41, vcc, 0, v41, vcc
	global_load_dwordx4 v[40:43], v[40:41], off offset:1024

; #define CMP_LOAD(tk_, AR, BR) do { const int t_ = (tk_); if (t_ < 32) { _Pragma("unroll") for (int i = 0; i < 4; ++i) AR[i] = *(const u32x4*)(asrc + (size_t)i * 64 * 2048 + t_ * 64); \
;         if (bthr) BR = *(const u32x4*)(bsrc + (size_t)t_ * NZ); } } while (0)
; DI void compress_task(LAS unsigned char* lds, const bf16_t* Z, const bf16_t* W1t, const bf16_t* W2t, const float* bias1, bf16_t* KCC, bf16_t* VCT, int kv, int b, int hk, int nt4, int tid, int wave, int lane) {
;     ...
;     f32x16 acc = f16zero();
;     CMP_LOAD(0, a0, b0v); CMP_LOAD(1, a1, b1v);
;     for (int tk = 0; tk < 32; tk += 2) { CMP_STEP(tk, a0, b0v, 0); CMP_STEP(tk + 1, a1, b1v, 1); }
.LBB0_398:
	v_add_u32_e32 v1, v79, v81
	ds_read_b128 v[94:97], v1
	v_add_u32_e32 v34, v80, v81
	ds_read_b128 v[98:101], v34 offset:32768
	v_add_u32_e32 v34, v79, v82
	v_add_u32_e32 v37, v80, v82
	v_add_u32_e32 v71, v80, v83
	v_add_u32_e32 v73, v80, v84
	s_waitcnt lgkmcnt(0)
	v_mfma_f32_32x32x16_bf16 v[2:17], v[94:97], v[98:101], v[2:17]
	ds_read_b128 v[94:97], v34
	ds_read_b128 v[98:101], v37 offset:32768
	v_add_u32_e32 v37, v79, v83
	s_waitcnt lgkmcnt(0)
	v_mfma_f32_32x32x16_bf16 v[2:17], v[94:97], v[98:101], v[2:17]
	ds_read_b128 v[94:97], v37
	ds_read_b128 v[98:101], v71 offset:32768
	v_add_u32_e32 v71, v79, v84
	s_waitcnt lgkmcnt(0)
	v_mfma_f32_32x32x16_bf16 v[2:17], v[94:97], v[98:101], v[2:17]
	ds_read_b128 v[94:97], v71
	ds_read_b128 v[98:101], v73 offset:32768
	ds_write_b128 v93, v[48:51] offset:36864
	ds_write_b128 v93, v[44:47] offset:45056
	ds_write_b128 v93, v[52:55] offset:53248
	ds_write_b128 v93, v[60:63] offset:61440
	s_waitcnt lgkmcnt(4)
	v_mfma_f32_32x32x16_bf16 v[2:17], v[94:97], v[98:101], v[2:17]
	s_and_saveexec_b64 s[10:11], s[4:5]
	v_add_u32_e32 v73, 0x11000, v93
	ds_write_b128 v73, v[56:59]
	s_or_b64 exec, exec, s[10:11]
	s_cmp_gt_u32 s12, 28
	s_waitcnt lgkmcnt(0)
	s_barrier
	s_cbranch_scc1 .LBB0_391
	v_add_co_u32_e32 v44, vcc, 0x40000, v76
	s_nop 1
	v_addc_co_u32_e32 v45, vcc, 0, v77, vcc
	v_add_co_u32_e32 v48, vcc, 0x80000, v76
	s_nop 1
	v_addc_co_u32_e32 v49, vcc, 0, v77, vcc
	v_add_co_u32_e32 v60, vcc, 0xc0000, v76
	global_load_dwordx4 v[44:47], v[44:45], off offset:384
	s_nop 0
	global_load_dwordx4 v[52:55], v[48:49], off offset:384
	v_addc_co_u32_e32 v61, vcc, 0, v77, vcc
	global_load_dwordx4 v[48:51], v[76:77], off offset:384
	s_nop 0
	global_load_dwordx4 v[60:63], v[60:61], off offset:384
	s_and_saveexec_b64 s[10:11], s[4:5]
	s_cbranch_execz .LBB0_390
	v_lshl_add_u64 v[56:57], v[38:39], 0, v[66:67]
	v_add_co_u32_e32 v56, vcc, 0xe206000, v56
	s_nop 1
	v_addc_co_u32_e32 v57, vcc, 0, v57, vcc
	global_load_dwordx4 v[56:59], v[56:57], off offset:1536
	s_branch .LBB0_390
.Lcmp_noload:
	s_waitcnt vmcnt(0)
	s_branch .LBB0_398

; DI void select_row(const float* SC, unsigned* dmask, int b, int t, int lane) {
;     ...
;             for (int e = 0; e < 4; ++e) { const unsigned bits = __builtin_bit_cast(unsigned, v[e] + 0.0f); const unsigned key = ((int)bits < 0) ? ~bits : (bits | 0x80000000u);
;                 u[k][e] = (256 * k + 4 * lane + e <= t) ? key : 0u; }
;         } else { u[k][0] = 0u; u[k][1] = 0u; u[k][2] = 0u; u[k][3] = 0u; }
;     }
;     ...
;     unsigned T = 0u; bool hit = false; int startbit = 31;
;     {
;         int cnt; SEL_COUNT(0xBF800000u, cnt);
.LBB0_549:
	s_waitcnt vmcnt(1)
	v_pk_add_f32 v[6:7], v[6:7], 0 op_sel_hi:[1,0]
	s_waitcnt vmcnt(0)
	v_pk_add_f32 v[2:3], v[2:3], 0 op_sel_hi:[1,0]
	v_and_b32_e32 v11, 0x7fffffff, v7
	v_and_b32_e32 v10, 0x7fffffff, v6
	v_xor_b32_e32 v1, -1, v7
	v_pk_add_f32 v[34:35], v[10:11], 0 neg_lo:[1,1] neg_hi:[1,1]
	v_cmp_gt_i32_e32 vcc, 0, v7
	v_xor_b32_e32 v75, -1, v6
	s_nop 0
	v_cndmask_b32_e32 v10, v35, v1, vcc
	v_cmp_gt_i32_e32 vcc, 0, v6
	v_pk_add_f32 v[6:7], v[8:9], 0 op_sel_hi:[1,0]
	s_nop 0
	v_and_b32_e32 v9, 0x7fffffff, v7
	v_and_b32_e32 v8, 0x7fffffff, v6
	v_cndmask_b32_e32 v11, v34, v75, vcc
	v_xor_b32_e32 v1, -1, v7
	v_pk_add_f32 v[8:9], v[8:9], 0 neg_lo:[1,1] neg_hi:[1,1]
	v_cmp_gt_i32_e32 vcc, 0, v7
	v_xor_b32_e32 v34, -1, v6
	v_and_b32_e32 v7, 0x7fffffff, v3
	v_cndmask_b32_e32 v9, v9, v1, vcc
	v_cmp_gt_i32_e32 vcc, 0, v6
	v_and_b32_e32 v6, 0x7fffffff, v2
	v_pk_add_f32 v[6:7], v[6:7], 0 neg_lo:[1,1] neg_hi:[1,1]
	v_cndmask_b32_e32 v121, v8, v34, vcc
	v_xor_b32_e32 v8, -1, v2
	v_cmp_gt_i32_e32 vcc, 0, v2
	v_xor_b32_e32 v1, -1, v3
	s_nop 0
	v_cndmask_b32_e32 v2, v6, v8, vcc
	v_cmp_gt_i32_e32 vcc, 0, v3
	s_nop 1
	v_cndmask_b32_e32 v1, v7, v1, vcc
	v_cmp_ge_u32_e32 vcc, s65, v83
	s_nop 1
	v_cndmask_b32_e32 v6, 0, v1, vcc
	v_cmp_ge_u32_e32 vcc, s65, v90
	s_nop 1
	v_cndmask_b32_e32 v7, 0, v2, vcc
	v_pk_add_f32 v[2:3], v[4:5], 0 op_sel_hi:[1,0]
	s_nop 0
	v_and_b32_e32 v5, 0x7fffffff, v3
	v_and_b32_e32 v4, 0x7fffffff, v2
	v_xor_b32_e32 v8, -1, v2
	v_pk_add_f32 v[4:5], v[4:5], 0 neg_lo:[1,1] neg_hi:[1,1]
	v_cmp_gt_i32_e32 vcc, 0, v2
	v_xor_b32_e32 v1, -1, v3
	s_nop 0
	v_cndmask_b32_e32 v2, v4, v8, vcc
	v_cmp_gt_i32_e32 vcc, 0, v3
	s_nop 1
	v_cndmask_b32_e32 v1, v5, v1, vcc
	v_cmp_ge_u32_e32 vcc, s65, v85
	s_nop 1
	v_cndmask_b32_e32 v5, 0, v1, vcc
	v_cmp_ge_u32_e32 vcc, s65, v92
	v_mov_b32_e32 v1, v43
	s_nop 0
	v_cndmask_b32_e32 v8, 0, v2, vcc
	v_cmp_le_u32_e32 vcc, s62, v11
	v_addc_co_u32_e32 v1, vcc, 0, v1, vcc
	v_cndmask_b32_e64 v2, 0, 1, s[10:11]
	v_cmp_le_u32_e32 vcc, s62, v10
	v_addc_co_u32_e32 v1, vcc, 0, v1, vcc
	v_cmp_ne_u32_e64 s[82:83], 1, v2
	v_cmp_le_u32_e32 vcc, s62, v121
	v_addc_co_u32_e32 v1, vcc, 0, v1, vcc
	v_cmp_le_u32_e32 vcc, s62, v9
	v_addc_co_u32_e32 v1, vcc, 0, v1, vcc
	v_cmp_le_u32_e32 vcc, s62, v7
	v_addc_co_u32_e32 v1, vcc, 0, v1, vcc
	v_cmp_le_u32_e32 vcc, s62, v6
	v_addc_co_u32_e32 v1, vcc, 0, v1, vcc
	v_cmp_le_u32_e32 vcc, s62, v8
	v_addc_co_u32_e32 v1, vcc, 0, v1, vcc
	v_cmp_le_u32_e32 vcc, s62, v5
	v_addc_co_u32_e32 v1, vcc, 0, v1, vcc
	s_andn2_b64 vcc, exec, s[10:11]
	s_cbranch_vccnz .LBB0_566
	v_cmp_le_u32_e32 vcc, s62, v33
	v_addc_co_u32_e32 v1, vcc, 0, v1, vcc
	v_cmp_le_u32_e32 vcc, s62, v41
	v_addc_co_u32_e32 v1, vcc, 0, v1, vcc
	v_cmp_le_u32_e32 vcc, s62, v32
	v_addc_co_u32_e32 v1, vcc, 0, v1, vcc
	v_cmp_le_u32_e32 vcc, s62, v42
	v_addc_co_u32_e32 v1, vcc, 0, v1, vcc
	v_cmp_le_u32_e32 vcc, s62, v29
	v_addc_co_u32_e32 v1, vcc, 0, v1, vcc
	v_cmp_le_u32_e32 vcc, s62, v30
	v_addc_co_u32_e32 v1, vcc, 0, v1, vcc
	v_cmp_le_u32_e32 vcc, s62, v28
	v_addc_co_u32_e32 v1, vcc, 0, v1, vcc
	v_cmp_le_u32_e32 vcc, s62, v31
	v_addc_co_u32_e32 v1, vcc, 0, v1, vcc
	v_cndmask_b32_e64 v2, 0, 1, s[76:77]
	v_cmp_ne_u32_e64 s[78:79], 1, v2
	s_andn2_b64 vcc, exec, s[76:77]
	s_cbranch_vccz .LBB0_567

; DI void select_row(const float* SC, unsigned* dmask, int b, int t, int lane) {
;     ...
;     unsigned T = 0u; bool hit = false; int startbit = 31;
;     {
;         int cnt; SEL_COUNT(0xBF800000u, cnt);
.LBB0_552:
	v_cmp_le_u32_e32 vcc, s62, v15
	v_addc_co_u32_e32 v1, vcc, 0, v1, vcc
	v_cmp_le_u32_e32 vcc, s62, v16
	v_addc_co_u32_e32 v1, vcc, 0, v1, vcc
	v_cmp_le_u32_e32 vcc, s62, v19
	v_addc_co_u32_e32 v1, vcc, 0, v1, vcc
	v_cmp_le_u32_e32 vcc, s62, v20
	v_addc_co_u32_e32 v1, vcc, 0, v1, vcc
	v_cmp_le_u32_e32 vcc, s62, v13
	v_addc_co_u32_e32 v1, vcc, 0, v1, vcc
	v_cmp_le_u32_e32 vcc, s62, v14
	v_addc_co_u32_e32 v1, vcc, 0, v1, vcc
	v_cmp_le_u32_e32 vcc, s62, v12
	v_addc_co_u32_e32 v1, vcc, 0, v1, vcc
	v_cmp_le_u32_e32 vcc, s62, v17
	v_addc_co_u32_e32 v1, vcc, 0, v1, vcc

; DI void select_row(const float* SC, unsigned* dmask, int b, int t, int lane) {
;     ...
;     unsigned T = 0u; bool hit = false; int startbit = 31;
;     {
;         int cnt; SEL_COUNT(0xBF800000u, cnt);
;         if (cnt < 256) {
; #pragma unroll 1
;             for (unsigned e = 0x7Eu; e >= 0x7Au; --e) {
;                 const unsigned cand = 0x80000000u | (e << 23); SEL_COUNT(cand, cnt);
;                 if (cnt >= 256) { T = cand; startbit = 22; hit = (cnt == 256); break; }
.LBB0_556:
	v_mov_b32_e32 v1, 0
	s_or_b32 s14, s81, 0x80000000
	v_cmp_le_u32_e32 vcc, s14, v11
	v_addc_co_u32_e32 v1, vcc, 0, v1, vcc
	v_cmp_le_u32_e32 vcc, s14, v10
	v_addc_co_u32_e32 v1, vcc, 0, v1, vcc
	v_cmp_le_u32_e32 vcc, s14, v121
	v_addc_co_u32_e32 v1, vcc, 0, v1, vcc
	v_cmp_le_u32_e32 vcc, s14, v9
	v_addc_co_u32_e32 v1, vcc, 0, v1, vcc
	v_cmp_le_u32_e32 vcc, s14, v7
	v_addc_co_u32_e32 v1, vcc, 0, v1, vcc
	v_cmp_le_u32_e32 vcc, s14, v6
	v_addc_co_u32_e32 v1, vcc, 0, v1, vcc
	v_cmp_le_u32_e32 vcc, s14, v8
	v_addc_co_u32_e32 v1, vcc, 0, v1, vcc
	v_cmp_le_u32_e32 vcc, s14, v5
	v_addc_co_u32_e32 v1, vcc, 0, v1, vcc
	s_and_b64 vcc, exec, s[82:83]
	s_cbranch_vccnz .LBB0_562
	v_cmp_le_u32_e32 vcc, s14, v33
	v_addc_co_u32_e32 v1, vcc, 0, v1, vcc
	v_cmp_le_u32_e32 vcc, s14, v41
	v_addc_co_u32_e32 v1, vcc, 0, v1, vcc
	v_cmp_le_u32_e32 vcc, s14, v32
	v_addc_co_u32_e32 v1, vcc, 0, v1, vcc
	v_cmp_le_u32_e32 vcc, s14, v42
	v_addc_co_u32_e32 v1, vcc, 0, v1, vcc
	v_cmp_le_u32_e32 vcc, s14, v29
	v_addc_co_u32_e32 v1, vcc, 0, v1, vcc
	v_cmp_le_u32_e32 vcc, s14, v30
	v_addc_co_u32_e32 v1, vcc, 0, v1, vcc
	v_cmp_le_u32_e32 vcc, s14, v28
	v_addc_co_u32_e32 v1, vcc, 0, v1, vcc
	v_cmp_le_u32_e32 vcc, s14, v31
	v_addc_co_u32_e32 v1, vcc, 0, v1, vcc
	s_and_b64 vcc, exec, s[78:79]
	s_cbranch_vccz .LBB0_563

; DI void select_row(const float* SC, unsigned* dmask, int b, int t, int lane) {
;     ...
;     unsigned T = 0u; bool hit = false; int startbit = 31;
;     {
;         int cnt; SEL_COUNT(0xBF800000u, cnt);
;         if (cnt < 256) {
; #pragma unroll 1
;             for (unsigned e = 0x7Eu; e >= 0x7Au; --e) {
;                 const unsigned cand = 0x80000000u | (e << 23); SEL_COUNT(cand, cnt);
;                 if (cnt >= 256) { T = cand; startbit = 22; hit = (cnt == 256); break; }
.LBB0_559:
	v_cmp_le_u32_e32 vcc, s14, v15
	v_addc_co_u32_e32 v1, vcc, 0, v1, vcc
	v_cmp_le_u32_e32 vcc, s14, v16
	v_addc_co_u32_e32 v1, vcc, 0, v1, vcc
	v_cmp_le_u32_e32 vcc, s14, v19
	v_addc_co_u32_e32 v1, vcc, 0, v1, vcc
	v_cmp_le_u32_e32 vcc, s14, v20
	v_addc_co_u32_e32 v1, vcc, 0, v1, vcc
	v_cmp_le_u32_e32 vcc, s14, v13
	v_addc_co_u32_e32 v1, vcc, 0, v1, vcc
	v_cmp_le_u32_e32 vcc, s14, v14
	v_addc_co_u32_e32 v1, vcc, 0, v1, vcc
	v_cmp_le_u32_e32 vcc, s14, v12
	v_addc_co_u32_e32 v1, vcc, 0, v1, vcc
	v_cmp_le_u32_e32 vcc, s14, v17
	v_addc_co_u32_e32 v1, vcc, 0, v1, vcc

; DI void select_row(const float* SC, unsigned* dmask, int b, int t, int lane) {
;     ...
;     unsigned T = 0u; bool hit = false; int startbit = 31;
;     {
;         int cnt; SEL_COUNT(0xBF800000u, cnt);
;         if (cnt < 256) {
; #pragma unroll 1
;             for (unsigned e = 0x7Eu; e >= 0x7Au; --e) {
;                 const unsigned cand = 0x80000000u | (e << 23); SEL_COUNT(cand, cnt);
;                 if (cnt >= 256) { T = cand; startbit = 22; hit = (cnt == 256); break; }
.LBB0_563:
	v_cmp_le_u32_e32 vcc, s14, v24
	v_addc_co_u32_e32 v1, vcc, 0, v1, vcc
	v_cmp_le_u32_e32 vcc, s14, v25
	v_addc_co_u32_e32 v1, vcc, 0, v1, vcc
	v_cmp_le_u32_e32 vcc, s14, v26
	v_addc_co_u32_e32 v1, vcc, 0, v1, vcc
	v_cmp_le_u32_e32 vcc, s14, v27
	v_addc_co_u32_e32 v1, vcc, 0, v1, vcc
	v_cmp_le_u32_e32 vcc, s14, v21
	v_addc_co_u32_e32 v1, vcc, 0, v1, vcc
	v_cmp_le_u32_e32 vcc, s14, v22
	v_addc_co_u32_e32 v1, vcc, 0, v1, vcc
	v_cmp_le_u32_e32 vcc, s14, v18
	v_addc_co_u32_e32 v1, vcc, 0, v1, vcc
	v_cmp_le_u32_e32 vcc, s14, v23
	v_addc_co_u32_e32 v1, vcc, 0, v1, vcc
	s_and_b64 vcc, exec, s[76:77]
	s_cbranch_vccz .LBB0_559
	s_branch .LBB0_560

; DI void select_row(const float* SC, unsigned* dmask, int b, int t, int lane) {
;     ...
;     unsigned T = 0u; bool hit = false; int startbit = 31;
;     {
;         int cnt; SEL_COUNT(0xBF800000u, cnt);
.LBB0_567:
	v_cmp_le_u32_e32 vcc, s62, v24
	v_addc_co_u32_e32 v1, vcc, 0, v1, vcc
	v_cmp_le_u32_e32 vcc, s62, v25
	v_addc_co_u32_e32 v1, vcc, 0, v1, vcc
	v_cmp_le_u32_e32 vcc, s62, v26
	v_addc_co_u32_e32 v1, vcc, 0, v1, vcc
	v_cmp_le_u32_e32 vcc, s62, v27
	v_addc_co_u32_e32 v1, vcc, 0, v1, vcc
	v_cmp_le_u32_e32 vcc, s62, v21
	v_addc_co_u32_e32 v1, vcc, 0, v1, vcc
	v_cmp_le_u32_e32 vcc, s62, v22
	v_addc_co_u32_e32 v1, vcc, 0, v1, vcc
	v_cmp_le_u32_e32 vcc, s62, v18
	v_addc_co_u32_e32 v1, vcc, 0, v1, vcc
	v_cmp_le_u32_e32 vcc, s62, v23
	v_addc_co_u32_e32 v1, vcc, 0, v1, vcc
	v_cndmask_b32_e64 v2, 0, 1, s[80:81]
	v_cmp_ne_u32_e64 s[76:77], 1, v2
	s_andn2_b64 vcc, exec, s[80:81]
	s_cbranch_vccz .LBB0_552
	s_branch .LBB0_553

; DI void select_row(const float* SC, unsigned* dmask, int b, int t, int lane) {
;     ...
;             const unsigned cand = T | (1u << bit); int cnt; SEL_COUNT(cand, cnt);
;             if (cnt >= 256) { T = cand; if (cnt == 256) { hit = true; break; } }
.LBB0_574:
	v_lshlrev_b32_e64 v2, v1, 1
	v_mov_b32_e32 v4, 0
	v_or_b32_e32 v2, v2, v3
	v_cmp_le_u32_e32 vcc, v2, v11
	v_addc_co_u32_e32 v4, vcc, 0, v4, vcc
	v_cmp_le_u32_e32 vcc, v2, v10
	v_addc_co_u32_e32 v4, vcc, 0, v4, vcc
	v_cmp_le_u32_e32 vcc, v2, v121
	v_addc_co_u32_e32 v4, vcc, 0, v4, vcc
	v_cmp_le_u32_e32 vcc, v2, v9
	v_addc_co_u32_e32 v4, vcc, 0, v4, vcc
	v_cmp_le_u32_e32 vcc, v2, v7
	v_addc_co_u32_e32 v4, vcc, 0, v4, vcc
	v_cmp_le_u32_e32 vcc, v2, v6
	v_addc_co_u32_e32 v4, vcc, 0, v4, vcc
	v_cmp_le_u32_e32 vcc, v2, v8
	v_addc_co_u32_e32 v4, vcc, 0, v4, vcc
	v_cmp_le_u32_e32 vcc, v2, v5
	v_addc_co_u32_e32 v4, vcc, 0, v4, vcc
	s_and_b64 vcc, exec, s[82:83]
	s_cbranch_vccnz .LBB0_580
	v_cmp_le_u32_e32 vcc, v2, v33
	v_addc_co_u32_e32 v4, vcc, 0, v4, vcc
	v_cmp_le_u32_e32 vcc, v2, v41
	v_addc_co_u32_e32 v4, vcc, 0, v4, vcc
	v_cmp_le_u32_e32 vcc, v2, v32
	v_addc_co_u32_e32 v4, vcc, 0, v4, vcc
	v_cmp_le_u32_e32 vcc, v2, v42
	v_addc_co_u32_e32 v4, vcc, 0, v4, vcc
	v_cmp_le_u32_e32 vcc, v2, v29
	v_addc_co_u32_e32 v4, vcc, 0, v4, vcc
	v_cmp_le_u32_e32 vcc, v2, v30
	v_addc_co_u32_e32 v4, vcc, 0, v4, vcc
	v_cmp_le_u32_e32 vcc, v2, v28
	v_addc_co_u32_e32 v4, vcc, 0, v4, vcc
	v_cmp_le_u32_e32 vcc, v2, v31
	v_addc_co_u32_e32 v4, vcc, 0, v4, vcc
	s_and_b64 vcc, exec, s[78:79]
	s_cbranch_vccz .LBB0_581

; DI void select_row(const float* SC, unsigned* dmask, int b, int t, int lane) {
;     ...
;             const unsigned cand = T | (1u << bit); int cnt; SEL_COUNT(cand, cnt);
;             if (cnt >= 256) { T = cand; if (cnt == 256) { hit = true; break; } }
.LBB0_577:
	v_cmp_le_u32_e32 vcc, v2, v15
	v_addc_co_u32_e32 v4, vcc, 0, v4, vcc
	v_cmp_le_u32_e32 vcc, v2, v16
	v_addc_co_u32_e32 v4, vcc, 0, v4, vcc
	v_cmp_le_u32_e32 vcc, v2, v19
	v_addc_co_u32_e32 v4, vcc, 0, v4, vcc
	v_cmp_le_u32_e32 vcc, v2, v20
	v_addc_co_u32_e32 v4, vcc, 0, v4, vcc
	v_cmp_le_u32_e32 vcc, v2, v13
	v_addc_co_u32_e32 v4, vcc, 0, v4, vcc
	v_cmp_le_u32_e32 vcc, v2, v14
	v_addc_co_u32_e32 v4, vcc, 0, v4, vcc
	v_cmp_le_u32_e32 vcc, v2, v12
	v_addc_co_u32_e32 v4, vcc, 0, v4, vcc
	v_cmp_le_u32_e32 vcc, v2, v17
	v_addc_co_u32_e32 v4, vcc, 0, v4, vcc

; DI void select_row(const float* SC, unsigned* dmask, int b, int t, int lane) {
;     ...
;             const unsigned cand = T | (1u << bit); int cnt; SEL_COUNT(cand, cnt);
;             if (cnt >= 256) { T = cand; if (cnt == 256) { hit = true; break; } }
.LBB0_581:
	v_cmp_le_u32_e32 vcc, v2, v24
	v_addc_co_u32_e32 v4, vcc, 0, v4, vcc
	v_cmp_le_u32_e32 vcc, v2, v25
	v_addc_co_u32_e32 v4, vcc, 0, v4, vcc
	v_cmp_le_u32_e32 vcc, v2, v26
	v_addc_co_u32_e32 v4, vcc, 0, v4, vcc
	v_cmp_le_u32_e32 vcc, v2, v27
	v_addc_co_u32_e32 v4, vcc, 0, v4, vcc
	v_cmp_le_u32_e32 vcc, v2, v21
	v_addc_co_u32_e32 v4, vcc, 0, v4, vcc
	v_cmp_le_u32_e32 vcc, v2, v22
	v_addc_co_u32_e32 v4, vcc, 0, v4, vcc
	v_cmp_le_u32_e32 vcc, v2, v18
	v_addc_co_u32_e32 v4, vcc, 0, v4, vcc
	v_cmp_le_u32_e32 vcc, v2, v23
	v_addc_co_u32_e32 v4, vcc, 0, v4, vcc
	s_and_b64 vcc, exec, s[76:77]
	s_cbranch_vccz .LBB0_577
	s_branch .LBB0_578

; #define LAS __attribute__((address_space(3)))
; #define MFMA32(a, b, c) __builtin_amdgcn_mfma_f32_32x32x16_bf16((a), (b), (c), 0, 0, 0)
; DI float half_max(float v) { return fmaxf(v, __shfl_xor(v, 32)); }
; DI void flash_qk_bias(const LAS unsigned char* kb, const bf16x8 (&qf)[4], f32x16& p0, f32x16& p1, int r32, int h, const bf16x8& m0, const bf16x8& m1, const bf16x8& ef) {
;     p0 = MFMA32(m0, ef, f16zero()); p1 = MFMA32(m1, ef, f16zero());
;     const int sw = (r32 >> 1) & 7;
; #pragma unroll
;     for (int s = 0; s < 4; ++s) {
;         const int off = r32 * 128 + (((2 * s + h) ^ sw) << 4);
;         const bf16x8 a0 = *(const LAS bf16x8*)(kb + off), a1 = *(const LAS bf16x8*)(kb + off + 4096);
;         p0 = MFMA32(a0, qf[s], p0); p1 = MFMA32(a1, qf[s], p1);
;     }
; }
; DI void flash_pv2(FState& sa, FState& sb, f32x16& a0, f32x16& a1, bool rona, f32x16& b0, f32x16& b1, bool ronb, const LAS unsigned char* va, const LAS unsigned char* vbb, int lane) {
;     float mxa = fmaxf(a0[0], a1[0]), mxb = fmaxf(b0[0], b1[0]);
; #pragma unroll
;     for (int r = 1; r < 16; ++r) { asm("v_max3_f32 %0, %1, %2, %3" : "=v"(mxa) : "v"(mxa), "v"(a0[r]), "v"(a1[r])); asm("v_max3_f32 %0, %1, %2, %3" : "=v"(mxb) : "v"(mxb), "v"(b0[r]), "v"(b1[r])); }
;     mxa = half_max(mxa); mxb = half_max(mxb);
;     mxa = rona ? mxa : NINF; mxb = ronb ? mxb : NINF;
;     const bool upa = mxa > sa.m + THR_RAW, upb = mxb > sb.m + THR_RAW;
.LBB0_726:
	s_or_b64 exec, exec, s[4:5]
	v_mov_b32_e32 v94, v90
	v_mov_b32_e32 v95, v90
	v_mov_b32_e32 v91, v90
	s_add_i32 s4, s16, 0xffff8000
	v_mov_b32_e32 v86, v90
	v_mov_b32_e32 v87, v90
	s_and_b32 s4, s4, 0x8000
	s_add_i32 s73, s4, 0
	v_mfma_f32_32x32x16_bf16 v[100:115], v[92:95], v[84:87], 0
	v_add_u32_e32 v99, s73, v201
	v_add_u32_e32 v179, v99, v165
	v_add_u32_e32 v187, v99, v216
	v_add_u32_e32 v192, v99, v217
	v_add_u32_e32 v193, v99, v218
	v_mov_b32_e32 v118, v98
	v_mov_b32_e32 v119, v98
	v_mfma_f32_32x32x16_bf16 v[68:83], v[88:91], v[84:87], 0
	ds_read_b128 v[88:91], v179
	ds_read_b128 v[92:95], v179 offset:4096
	v_mov_b32_e32 v99, v98
	s_cmp_lt_u32 s51, s71
	s_cselect_b64 s[4:5], -1, 0
	s_waitcnt lgkmcnt(0)
	v_mfma_f32_32x32x16_bf16 v[100:115], v[88:91], v[132:135], v[100:115]
	v_mfma_f32_32x32x16_bf16 v[68:83], v[92:95], v[132:135], v[68:83]
	ds_read_b128 v[88:91], v187
	ds_read_b128 v[92:95], v187 offset:4096
	s_waitcnt lgkmcnt(0)
	v_mfma_f32_32x32x16_bf16 v[100:115], v[88:91], v[136:139], v[100:115]
	v_mfma_f32_32x32x16_bf16 v[68:83], v[92:95], v[136:139], v[68:83]
	ds_read_b128 v[88:91], v192
	ds_read_b128 v[92:95], v192 offset:4096
	s_waitcnt lgkmcnt(0)
	v_mfma_f32_32x32x16_bf16 v[100:115], v[88:91], v[140:143], v[100:115]
	v_mfma_f32_32x32x16_bf16 v[68:83], v[92:95], v[140:143], v[68:83]
	ds_read_b128 v[88:91], v193
	ds_read_b128 v[92:95], v193 offset:4096
	ds_read_b128 v[182:185], v179 offset:16384
	ds_read_b128 v[188:191], v179 offset:20480
	v_mfma_f32_32x32x16_bf16 v[116:131], v[116:119], v[84:87], 0
	s_waitcnt lgkmcnt(0)
	v_mfma_f32_32x32x16_bf16 v[100:115], v[88:91], v[144:147], v[100:115]
	v_mfma_f32_32x32x16_bf16 v[68:83], v[92:95], v[144:147], v[68:83]
	v_mfma_f32_32x32x16_bf16 v[84:99], v[96:99], v[84:87], 0
	s_nop 10
	v_max_f32_e32 v179, v68, v68
	v_mfma_f32_32x32x16_bf16 v[116:131], v[182:185], v[132:135], v[116:131]
	v_mfma_f32_32x32x16_bf16 v[84:99], v[188:191], v[132:135], v[84:99]
	ds_read_b128 v[182:185], v187 offset:16384
	ds_read_b128 v[188:191], v187 offset:20480
	v_max_f32_e32 v187, v100, v100
	v_max_f32_e32 v179, v187, v179
	v_max3_f32 v179, v179, v101, v69
	v_max3_f32 v179, v179, v102, v70
	s_waitcnt lgkmcnt(0)
	v_mfma_f32_32x32x16_bf16 v[116:131], v[182:185], v[136:139], v[116:131]
	v_max3_f32 v179, v179, v103, v71
	v_max3_f32 v179, v179, v104, v72
	v_max3_f32 v179, v179, v105, v73
	v_max3_f32 v179, v179, v106, v74
	v_mfma_f32_32x32x16_bf16 v[84:99], v[188:191], v[136:139], v[84:99]
	ds_read_b128 v[182:185], v192 offset:16384
	ds_read_b128 v[188:191], v192 offset:20480
	v_max3_f32 v179, v179, v107, v75
	v_max3_f32 v179, v179, v108, v76
	v_max3_f32 v179, v179, v109, v77
	s_waitcnt lgkmcnt(0)
	v_mfma_f32_32x32x16_bf16 v[116:131], v[182:185], v[140:143], v[116:131]
	ds_read_b128 v[182:185], v193 offset:20480
	v_max3_f32 v179, v179, v110, v78
	v_max3_f32 v179, v179, v111, v79
	v_max3_f32 v179, v179, v112, v80
	v_mfma_f32_32x32x16_bf16 v[84:99], v[188:191], v[140:143], v[84:99]
	v_max3_f32 v179, v179, v113, v81
	v_max3_f32 v179, v179, v114, v82
	s_waitcnt lgkmcnt(0)
	v_mfma_f32_32x32x16_bf16 v[84:99], v[182:185], v[144:147], v[84:99]
	ds_read_b128 v[182:185], v193 offset:16384
	s_waitcnt lgkmcnt(0)
	v_mfma_f32_32x32x16_bf16 v[116:131], v[182:185], v[144:147], v[116:131]
	s_nop 8
	v_max_f32_e32 v187, v84, v84
	v_and_b32_e32 v184, 64, v198
	v_max3_f32 v183, v179, v115, v83
	v_xor_b32_e32 v179, 32, v198
	v_add_u32_e32 v184, 64, v184
	v_cmp_lt_i32_e32 vcc, v179, v184
	v_max_f32_e32 v182, v116, v116
	v_max_f32_e32 v182, v182, v187
	v_max3_f32 v182, v182, v117, v85
	v_cndmask_b32_e32 v179, v198, v179, vcc
	v_max3_f32 v182, v182, v118, v86
	v_lshlrev_b32_e32 v179, 2, v179
	v_max3_f32 v182, v182, v119, v87
	ds_bpermute_b32 v184, v179, v183
	v_max3_f32 v182, v182, v120, v88
	v_max3_f32 v182, v182, v121, v89
	v_max3_f32 v182, v182, v122, v90
	v_max3_f32 v182, v182, v123, v91
	v_max3_f32 v182, v182, v124, v92
	v_max3_f32 v182, v182, v125, v93
	v_max3_f32 v182, v182, v126, v94
	v_max3_f32 v182, v182, v127, v95
	v_max3_f32 v182, v182, v128, v96
	v_max3_f32 v182, v182, v129, v97
	v_max3_f32 v182, v182, v130, v98
	v_max3_f32 v185, v182, v131, v99
	ds_bpermute_b32 v187, v179, v185
	v_max_f32_e32 v182, v183, v183
	s_waitcnt lgkmcnt(0)
	v_max_f32_e32 v183, v184, v184
	v_max_f32_e32 v182, v182, v183
	v_max_f32_e32 v183, v185, v185
	v_max_f32_e32 v184, v187, v187
	v_max_f32_e32 v183, v183, v184
	v_cndmask_b32_e64 v183, v186, v183, s[4:5]
	v_pk_add_f32 v[184:185], v[180:181], s[46:47] op_sel_hi:[1,0]
	s_nop 0
	v_cmp_gt_f32_e64 s[6:7], v182, v184
	v_cmp_gt_f32_e64 s[8:9], v183, v185
	s_or_b64 vcc, s[6:7], s[8:9]
	s_cbranch_vccz .LBB0_728
; DI float fexp2(float x) { return __builtin_amdgcn_exp2f(x); }
; DI void flash_pv2(FState& sa, FState& sb, f32x16& a0, f32x16& a1, bool rona, f32x16& b0, f32x16& b1, bool ronb, const LAS unsigned char* va, const LAS unsigned char* vbb, int lane) {
;     ...
;     if (__any(upa || upb)) {
;         const float mna = upa ? mxa : sa.m, mnb = upb ? mxb : sb.m;
;         const float ala = upa ? fexp2((sa.m - mna) * SM_C) : 1.0f, alb = upb ? fexp2((sb.m - mnb) * SM_C) : 1.0f;
;         sa.m = mna; sa.l *= ala; sb.m = mnb; sb.l *= alb;
; #pragma unroll
;         for (int r = 0; r < 16; ++r) { sa.o0[r] *= ala; sa.o1[r] *= ala; sb.o0[r] *= alb; sb.o1[r] *= alb; }
;     }
	v_cndmask_b32_e64 v183, v181, v183, s[8:9]
	v_cndmask_b32_e64 v182, v180, v182, s[6:7]
	v_pk_add_f32 v[180:181], v[180:181], v[182:183] neg_lo:[0,1] neg_hi:[0,1]
	s_nop 0
	v_mul_f32_e32 v180, 0x3e38aa3b, v180
	v_mul_f32_e32 v181, 0x3e38aa3b, v181
	v_exp_f32_e32 v181, v181
	v_exp_f32_e32 v180, v180
	v_cndmask_b32_e64 v181, 1.0, v181, s[8:9]
	v_cndmask_b32_e64 v180, 1.0, v180, s[6:7]
	v_pk_mul_f32 v[172:173], v[172:173], v[180:181]
	v_pk_mul_f32 v[66:67], v[66:67], v[180:181] op_sel_hi:[1,0]
	v_pk_mul_f32 v[64:65], v[64:65], v[180:181] op_sel_hi:[1,0]
	v_pk_mul_f32 v[62:63], v[62:63], v[180:181] op_sel_hi:[1,0]
	v_pk_mul_f32 v[60:61], v[60:61], v[180:181] op_sel_hi:[1,0]
	v_pk_mul_f32 v[58:59], v[58:59], v[180:181] op_sel_hi:[1,0]
	v_pk_mul_f32 v[56:57], v[56:57], v[180:181] op_sel_hi:[1,0]
	v_pk_mul_f32 v[54:55], v[54:55], v[180:181] op_sel_hi:[1,0]
	v_pk_mul_f32 v[52:53], v[52:53], v[180:181] op_sel_hi:[1,0]
	v_pk_mul_f32 v[18:19], v[18:19], v[180:181] op_sel_hi:[1,0]
	v_pk_mul_f32 v[16:17], v[16:17], v[180:181] op_sel_hi:[1,0]
	v_pk_mul_f32 v[14:15], v[14:15], v[180:181] op_sel_hi:[1,0]
	v_pk_mul_f32 v[12:13], v[12:13], v[180:181] op_sel_hi:[1,0]
	v_pk_mul_f32 v[10:11], v[10:11], v[180:181] op_sel_hi:[1,0]
	v_pk_mul_f32 v[8:9], v[8:9], v[180:181] op_sel_hi:[1,0]
	v_pk_mul_f32 v[6:7], v[6:7], v[180:181] op_sel_hi:[1,0]
	v_pk_mul_f32 v[4:5], v[4:5], v[180:181] op_sel_hi:[1,0]
	v_mov_b32_e32 v180, v181
	v_pk_mul_f32 v[50:51], v[50:51], v[180:181] op_sel_hi:[1,0]
	v_pk_mul_f32 v[48:49], v[48:49], v[180:181] op_sel_hi:[1,0]
	v_pk_mul_f32 v[46:47], v[46:47], v[180:181] op_sel_hi:[1,0]
	v_pk_mul_f32 v[44:45], v[44:45], v[180:181] op_sel_hi:[1,0]
	v_pk_mul_f32 v[42:43], v[42:43], v[180:181] op_sel_hi:[1,0]
	v_pk_mul_f32 v[40:41], v[40:41], v[180:181] op_sel_hi:[1,0]
	v_pk_mul_f32 v[38:39], v[38:39], v[180:181] op_sel_hi:[1,0]
	v_pk_mul_f32 v[36:37], v[36:37], v[180:181] op_sel_hi:[1,0]
	v_pk_mul_f32 v[34:35], v[34:35], v[180:181] op_sel_hi:[1,0]
	v_pk_mul_f32 v[32:33], v[32:33], v[180:181] op_sel_hi:[1,0]
	v_pk_mul_f32 v[30:31], v[30:31], v[180:181] op_sel_hi:[1,0]
	v_pk_mul_f32 v[28:29], v[28:29], v[180:181] op_sel_hi:[1,0]
	v_pk_mul_f32 v[26:27], v[26:27], v[180:181] op_sel_hi:[1,0]
	v_pk_mul_f32 v[24:25], v[24:25], v[180:181] op_sel_hi:[1,0]
	v_pk_mul_f32 v[22:23], v[22:23], v[180:181] op_sel_hi:[1,0]
	v_pk_mul_f32 v[20:21], v[20:21], v[180:181] op_sel_hi:[1,0]
	v_mov_b64_e32 v[180:181], v[182:183]

; DI float fexp2(float x) { return __builtin_amdgcn_exp2f(x); }
; DI float half_max(float v) { return fmaxf(v, __shfl_xor(v, 32)); }
; DI void flash_pv(FState& st, f32x16& p0, f32x16& p1, bool rowon, const LAS unsigned char* vb, int lane) {
;     float mx = fmaxf(p0[0], p1[0]);
; #pragma unroll
;     for (int r = 1; r < 16; ++r) asm("v_max3_f32 %0, %1, %2, %3" : "=v"(mx) : "v"(mx), "v"(p0[r]), "v"(p1[r]));
;     mx = half_max(mx);
;     mx = rowon ? mx : NINF;
;     const bool upd = mx > st.m + THR_RAW;
;     if (__any(upd)) {
;         const float mn = upd ? mx : st.m;
;         const float alpha = upd ? fexp2((st.m - mn) * SM_C) : 1.0f;
;         st.m = mn; st.l *= alpha;
; #pragma unroll
;         for (int r = 0; r < 16; ++r) { st.o0[r] *= alpha; st.o1[r] *= alpha; }
;     }
.LBB0_753:
	v_max_f32_e32 v2, v82, v82
	v_max_f32_e32 v4, v98, v98
	v_max_f32_e32 v2, v4, v2
	v_max3_f32 v2, v2, v99, v83
	v_and_b32_e32 v5, 64, v198
	v_max3_f32 v2, v2, v100, v84
	v_xor_b32_e32 v4, 32, v198
	v_max3_f32 v2, v2, v101, v85
	v_add_u32_e32 v5, 64, v5
	v_max3_f32 v2, v2, v102, v86
	v_cmp_lt_i32_e32 vcc, v4, v5
	v_max3_f32 v2, v2, v103, v87
	v_max3_f32 v2, v2, v104, v88
	v_max3_f32 v2, v2, v105, v89
	v_cndmask_b32_e32 v4, v198, v4, vcc
	v_max3_f32 v2, v2, v106, v90
	v_lshlrev_b32_e32 v215, 2, v4
	v_max3_f32 v2, v2, v107, v91
	v_max3_f32 v2, v2, v108, v92
	v_max3_f32 v2, v2, v109, v93
	v_max3_f32 v2, v2, v110, v94
	v_max3_f32 v2, v2, v111, v95
	v_max3_f32 v2, v2, v112, v96
	v_max3_f32 v2, v2, v113, v97
	ds_bpermute_b32 v4, v215, v2
	v_max_f32_e32 v2, v2, v2
	s_waitcnt lgkmcnt(0)
	v_max_f32_e32 v4, v4, v4
	v_max_f32_e32 v2, v2, v4
	v_cndmask_b32_e64 v2, v186, v2, s[8:9]
	v_add_f32_e32 v4, 0x42317218, v216
	v_cmp_gt_f32_e32 vcc, v2, v4
	s_cbranch_vccz .LBB0_755
	s_nop 0
	v_cndmask_b32_e32 v4, v216, v2, vcc
	v_sub_f32_e32 v2, v216, v4
	v_mul_f32_e32 v2, 0x3e38aa3b, v2
	v_exp_f32_e32 v2, v2
	v_mov_b32_e32 v216, v4
	v_cndmask_b32_e32 v2, 1.0, v2, vcc
	v_mul_f32_e32 v214, v214, v2
	v_pk_mul_f32 v[80:81], v[80:81], v[2:3] op_sel_hi:[1,0]
	v_pk_mul_f32 v[78:79], v[78:79], v[2:3] op_sel_hi:[1,0]
	v_pk_mul_f32 v[76:77], v[76:77], v[2:3] op_sel_hi:[1,0]
	v_pk_mul_f32 v[74:75], v[74:75], v[2:3] op_sel_hi:[1,0]
	v_pk_mul_f32 v[72:73], v[72:73], v[2:3] op_sel_hi:[1,0]
	v_pk_mul_f32 v[70:71], v[70:71], v[2:3] op_sel_hi:[1,0]
	v_pk_mul_f32 v[68:69], v[68:69], v[2:3] op_sel_hi:[1,0]
	v_pk_mul_f32 v[66:67], v[66:67], v[2:3] op_sel_hi:[1,0]
	v_pk_mul_f32 v[64:65], v[64:65], v[2:3] op_sel_hi:[1,0]
	v_pk_mul_f32 v[62:63], v[62:63], v[2:3] op_sel_hi:[1,0]
	v_pk_mul_f32 v[60:61], v[60:61], v[2:3] op_sel_hi:[1,0]
	v_pk_mul_f32 v[58:59], v[58:59], v[2:3] op_sel_hi:[1,0]
	v_pk_mul_f32 v[56:57], v[56:57], v[2:3] op_sel_hi:[1,0]
	v_pk_mul_f32 v[54:55], v[54:55], v[2:3] op_sel_hi:[1,0]
	v_pk_mul_f32 v[52:53], v[52:53], v[2:3] op_sel_hi:[1,0]
	v_pk_mul_f32 v[50:51], v[50:51], v[2:3] op_sel_hi:[1,0]

; DI float fexp2(float x) { return __builtin_amdgcn_exp2f(x); }
; DI float half_max(float v) { return fmaxf(v, __shfl_xor(v, 32)); }
; DI void flash_pv(FState& st, f32x16& p0, f32x16& p1, bool rowon, const LAS unsigned char* vb, int lane) {
;     float mx = fmaxf(p0[0], p1[0]);
; #pragma unroll
;     for (int r = 1; r < 16; ++r) asm("v_max3_f32 %0, %1, %2, %3" : "=v"(mx) : "v"(mx), "v"(p0[r]), "v"(p1[r]));
;     mx = half_max(mx);
;     mx = rowon ? mx : NINF;
;     const bool upd = mx > st.m + THR_RAW;
;     if (__any(upd)) {
;         const float mn = upd ? mx : st.m;
;         const float alpha = upd ? fexp2((st.m - mn) * SM_C) : 1.0f;
;         st.m = mn; st.l *= alpha;
; #pragma unroll
;         for (int r = 0; r < 16; ++r) { st.o0[r] *= alpha; st.o1[r] *= alpha; }
;     }
.LBB0_772:
	v_max_f32_e32 v2, v82, v82
	v_max_f32_e32 v4, v98, v98
	v_max_f32_e32 v2, v4, v2
	v_max3_f32 v2, v2, v99, v83
	v_max3_f32 v2, v2, v100, v84
	v_max3_f32 v2, v2, v101, v85
	v_max3_f32 v2, v2, v102, v86
	v_max3_f32 v2, v2, v103, v87
	v_max3_f32 v2, v2, v104, v88
	v_max3_f32 v2, v2, v105, v89
	v_max3_f32 v2, v2, v106, v90
	v_max3_f32 v2, v2, v107, v91
	v_max3_f32 v2, v2, v108, v92
	v_max3_f32 v2, v2, v109, v93
	v_max3_f32 v2, v2, v110, v94
	v_max3_f32 v2, v2, v111, v95
	v_max3_f32 v2, v2, v112, v96
	v_max3_f32 v2, v2, v113, v97
	ds_bpermute_b32 v4, v215, v2
	v_max_f32_e32 v2, v2, v2
	s_waitcnt lgkmcnt(0)
	v_max_f32_e32 v4, v4, v4
	v_max_f32_e32 v2, v2, v4
	v_cndmask_b32_e64 v2, v186, v2, s[8:9]
	v_add_f32_e32 v4, 0x42317218, v216
	v_cmp_gt_f32_e32 vcc, v2, v4
	s_cbranch_vccz .LBB0_774
	s_nop 0
	v_cndmask_b32_e32 v4, v216, v2, vcc
	v_sub_f32_e32 v2, v216, v4
	v_mul_f32_e32 v2, 0x3e38aa3b, v2
	v_exp_f32_e32 v2, v2
	v_mov_b32_e32 v216, v4
	v_cndmask_b32_e32 v2, 1.0, v2, vcc
	v_mul_f32_e32 v214, v214, v2
	v_pk_mul_f32 v[80:81], v[80:81], v[2:3] op_sel_hi:[1,0]
	v_pk_mul_f32 v[78:79], v[78:79], v[2:3] op_sel_hi:[1,0]
	v_pk_mul_f32 v[76:77], v[76:77], v[2:3] op_sel_hi:[1,0]
	v_pk_mul_f32 v[74:75], v[74:75], v[2:3] op_sel_hi:[1,0]
	v_pk_mul_f32 v[72:73], v[72:73], v[2:3] op_sel_hi:[1,0]
	v_pk_mul_f32 v[70:71], v[70:71], v[2:3] op_sel_hi:[1,0]
	v_pk_mul_f32 v[68:69], v[68:69], v[2:3] op_sel_hi:[1,0]
	v_pk_mul_f32 v[66:67], v[66:67], v[2:3] op_sel_hi:[1,0]
	v_pk_mul_f32 v[64:65], v[64:65], v[2:3] op_sel_hi:[1,0]
	v_pk_mul_f32 v[62:63], v[62:63], v[2:3] op_sel_hi:[1,0]
	v_pk_mul_f32 v[60:61], v[60:61], v[2:3] op_sel_hi:[1,0]
	v_pk_mul_f32 v[58:59], v[58:59], v[2:3] op_sel_hi:[1,0]
	v_pk_mul_f32 v[56:57], v[56:57], v[2:3] op_sel_hi:[1,0]
	v_pk_mul_f32 v[54:55], v[54:55], v[2:3] op_sel_hi:[1,0]
	v_pk_mul_f32 v[52:53], v[52:53], v[2:3] op_sel_hi:[1,0]
	v_pk_mul_f32 v[50:51], v[50:51], v[2:3] op_sel_hi:[1,0]
